# FFN-up GEMM phase: odd workgroups start ~4 us late (s_sleep) so that epilogue store bursts and K-loops of the two workgroup halves alternate
# baseline (speedup 1.0000x reference)
.LBB0_1383:
	s_or_b64 exec, exec, s[0:1]
	v_mov_b32_e32 v10, v0
	s_waitcnt lgkmcnt(0)
	s_barrier
	v_readlane_b32 s0, v253, 21
	s_nop 3
	s_bitcmp1_b32 s0, 0
	s_cbranch_scc0 .Lp13_nostag
	s_sleep 127
.Lp13_nostag:
	s_cmpk_gt_i32 s92, 0x7ff
	v_readfirstlane_b32 s10, v10
	s_cbranch_scc1 .LBB0_1407
	s_ashr_i32 s19, s92, 31
	s_lshr_b32 s0, s19, 29
	s_add_i32 s3, s92, s0
	s_and_b32 s0, s3, -8
	s_sub_i32 s4, s92, s0
	s_cmp_gt_i32 s4, -1
	s_cbranch_scc0 .LBB0_1386
	s_lshl_b32 s2, s4, 8
	s_cbranch_execz .LBB0_1387
	s_branch .LBB0_1388
